# norm wait relaxations for s=2 and phase-1 copies, ssd_combine early wait moved to loop bottom
# speedup vs baseline: 1.0406x; 1.0033x over previous
; __device__ __forceinline__ void norm_phase(const NormCfg& cf, int wvi) {
;     ...
;   float gpo[2][8], gpr[2][8], gate[2][8], sh[2][8], sc[2][8];
; #pragma unroll
;   for (int i = 0; i < 2; ++i) {
; #pragma unroll
;     for (int k = 0; k < 8; ++k) { gpo[i][k] = 0.f; gpr[i][k] = 0.f; gate[i][k] = 0.f; sh[i][k] = 0.f; sc[i][k] = 0.f; }
;     if (has_post) ld8(cf.g_post, i, gpo[i]);
;     if (has_pre) ld8(cf.g_pre, i, gpr[i]);
;   }
;   int cur_m = -1;
;   struct RowRegs { float4 xn[2][2]; u32x4 xb[2], yn[2]; };
;   RowRegs Q0, Q1;
;   auto fetch = [&](int row, RowRegs& Q) {
;     if (src32) {
;       const float* src = (row < TL) ? cf.src_lat + (size_t)row * DM : cf.src_ctx + (size_t)(row - TL) * DM;
; #pragma unroll
;       for (int i = 0; i < 2; ++i) {
;         Q.xn[i][0] = reinterpret_cast<const float4*>(src)[2 * (lane + 64 * i)];
;         Q.xn[i][1] = reinterpret_cast<const float4*>(src)[2 * (lane + 64 * i) + 1];
;       }
;     } else {
;       const u32x4* xp = reinterpret_cast<const u32x4*>(cf.xs + (size_t)row * DM);
; #pragma unroll
;       for (int i = 0; i < 2; ++i) Q.xb[i] = xp[lane + 64 * i];
;     }
;     if (has_post) {
;       const u32x4* yp = reinterpret_cast<const u32x4*>(cf.y + (size_t)row * DM);
; #pragma unroll
;       for (int i = 0; i < 2; ++i) Q.yn[i] = yp[lane + 64 * i];
;     }
;   };
;   fetch(r0, Q0);
;   if (r0 + 8 < r1) fetch(r0 + 8, Q1);
;   for (int row = r0; row < r1; row += 8) {
;     float xv[2][8], yv[2][8];
; #pragma unroll
;     for (int i = 0; i < 2; ++i) {
;       if (src32) {
;         xv[i][0] = Q0.xn[i][0].x; xv[i][1] = Q0.xn[i][0].y; xv[i][2] = Q0.xn[i][0].z; xv[i][3] = Q0.xn[i][0].w;
;         xv[i][4] = Q0.xn[i][1].x; xv[i][5] = Q0.xn[i][1].y; xv[i][6] = Q0.xn[i][1].z; xv[i][7] = Q0.xn[i][1].w;
;       } else unpack8(Q0.xb[i], xv[i]);
;       unpack8(Q0.yn[i], yv[i]);
;     }
;     Q0 = Q1;
;     if (row + 16 < r1) fetch(row + 16, Q1);
.LBB0_25:
	s_or_b64 exec, exec, s[2:3]
	v_readlane_b32 s0, v246, 24
	v_readlane_b32 s1, v246, 25
	v_lshlrev_b64 v[58:59], 11, v[120:121]
	v_or_b32_e32 v56, 0x80, v122
	v_lshl_add_u64 v[124:125], s[0:1], 0, v[176:177]
	v_readlane_b32 s0, v247, 63
	v_or_b32_e32 v58, v58, v176
	v_readlane_b32 s1, v246, 0
	v_mov_b32_e32 v176, v177
	v_mov_b32_e32 v121, -1
	v_lshl_add_u64 v[126:127], s[0:1], 0, v[58:59]
	s_mov_b64 s[14:15], 0
	v_lshlrev_b32_e32 v128, 4, v56
	v_mov_b64_e32 v[58:59], v[176:177]
	v_mov_b64_e32 v[66:67], v[176:177]
	v_mov_b64_e32 v[56:57], v[176:177]
	v_mov_b64_e32 v[64:65], v[176:177]
	v_mov_b64_e32 v[62:63], v[176:177]
	v_mov_b64_e32 v[74:75], v[176:177]
	v_mov_b64_e32 v[60:61], v[176:177]
	v_mov_b64_e32 v[72:73], v[176:177]
	v_mov_b64_e32 v[70:71], v[176:177]
	v_mov_b64_e32 v[82:83], v[176:177]
	v_mov_b64_e32 v[68:69], v[176:177]
	v_mov_b64_e32 v[80:81], v[176:177]
	v_mov_b64_e32 v[78:79], v[176:177]
	v_mov_b64_e32 v[86:87], v[176:177]
	v_mov_b64_e32 v[76:77], v[176:177]
	v_mov_b64_e32 v[84:85], v[176:177]
	v_readlane_b32 s2, v246, 26
	v_readlane_b32 s3, v246, 27
	s_waitcnt vmcnt(0)
	s_branch .LBB0_27
.LBB0_26:
	v_add_u32_e32 v120, 8, v120
	v_mov_b64_e32 v[94:95], v[54:55]
	v_mov_b64_e32 v[110:111], v[50:51]
	v_cmp_ge_i32_e32 vcc, v120, v123
	v_mov_b64_e32 v[92:93], v[52:53]
	v_mov_b64_e32 v[108:109], v[48:49]
	s_waitcnt vmcnt(2)
	v_mov_b64_e32 v[52:53], v[116:117]
	v_mov_b64_e32 v[48:49], v[112:113]
	v_lshl_add_u64 v[126:127], v[126:127], 0, s[84:85]
	s_or_b64 s[14:15], vcc, s[14:15]
	v_mov_b64_e32 v[54:55], v[118:119]
	v_mov_b64_e32 v[50:51], v[114:115]
	v_mov_b64_e32 v[22:23], v[38:39]
	v_mov_b64_e32 v[38:39], v[106:107]
	v_mov_b64_e32 v[20:21], v[36:37]
	v_mov_b64_e32 v[36:37], v[104:105]
	v_mov_b64_e32 v[26:27], v[34:35]
	v_mov_b64_e32 v[34:35], v[98:99]
	v_mov_b64_e32 v[24:25], v[32:33]
	v_mov_b64_e32 v[32:33], v[96:97]
	v_mov_b64_e32 v[18:19], v[46:47]
	v_mov_b64_e32 v[46:47], v[102:103]
	v_mov_b64_e32 v[16:17], v[44:45]
	v_mov_b64_e32 v[44:45], v[100:101]
	v_mov_b64_e32 v[30:31], v[42:43]
	v_mov_b64_e32 v[42:43], v[90:91]
	v_mov_b64_e32 v[28:29], v[40:41]
	v_mov_b64_e32 v[40:41], v[88:89]
	s_andn2_b64 exec, exec, s[14:15]
	s_cbranch_execz .LBB0_47

; __device__ __forceinline__ void norm_phase(const NormCfg& cf, int wvi) {
;     ...
;   auto fetch = [&](int row, RowRegs& Q) {
;     if (src32) {
;       const float* src = (row < TL) ? cf.src_lat + (size_t)row * DM : cf.src_ctx + (size_t)(row - TL) * DM;
; #pragma unroll
;       for (int i = 0; i < 2; ++i) {
;         Q.xn[i][0] = reinterpret_cast<const float4*>(src)[2 * (lane + 64 * i)];
;         Q.xn[i][1] = reinterpret_cast<const float4*>(src)[2 * (lane + 64 * i) + 1];
;       }
;     } else {
;       const u32x4* xp = reinterpret_cast<const u32x4*>(cf.xs + (size_t)row * DM);
; #pragma unroll
;       for (int i = 0; i < 2; ++i) Q.xb[i] = xp[lane + 64 * i];
;     }
;     if (has_post) {
;       const u32x4* yp = reinterpret_cast<const u32x4*>(cf.y + (size_t)row * DM);
; #pragma unroll
;       for (int i = 0; i < 2; ++i) Q.yn[i] = yp[lane + 64 * i];
;     }
;   };
;   fetch(r0, Q0);
;   if (r0 + 8 < r1) fetch(r0 + 8, Q1);
;   for (int row = r0; row < r1; row += 8) {
;     float xv[2][8], yv[2][8];
; #pragma unroll
;     for (int i = 0; i < 2; ++i) {
;       if (src32) {
;         xv[i][0] = Q0.xn[i][0].x; xv[i][1] = Q0.xn[i][0].y; xv[i][2] = Q0.xn[i][0].z; xv[i][3] = Q0.xn[i][0].w;
;         xv[i][4] = Q0.xn[i][1].x; xv[i][5] = Q0.xn[i][1].y; xv[i][6] = Q0.xn[i][1].z; xv[i][7] = Q0.xn[i][1].w;
;       } else unpack8(Q0.xb[i], xv[i]);
;       unpack8(Q0.yn[i], yv[i]);
;     }
;     Q0 = Q1;
;     if (row + 16 < r1) fetch(row + 16, Q1);
.LBB0_29:
	s_nop 0
	v_add_u32_e32 v92, 16, v120
	v_mov_b64_e32 v[114:115], v[50:51]
	v_mov_b64_e32 v[118:119], v[54:55]
	v_cmp_lt_i32_e32 vcc, v92, v123
	v_mov_b64_e32 v[112:113], v[48:49]
	v_mov_b64_e32 v[116:117], v[52:53]
	v_mov_b64_e32 v[106:107], v[38:39]
	v_mov_b64_e32 v[104:105], v[36:37]
	v_mov_b64_e32 v[98:99], v[34:35]
	v_mov_b64_e32 v[96:97], v[32:33]
	v_mov_b64_e32 v[102:103], v[46:47]
	v_mov_b64_e32 v[100:101], v[44:45]
	v_mov_b64_e32 v[90:91], v[42:43]
	v_mov_b64_e32 v[88:89], v[40:41]
	s_and_saveexec_b64 s[2:3], vcc
	s_cbranch_execz .LBB0_34
	s_mov_b64 s[8:9], -1
	s_and_b64 vcc, exec, s[6:7]
	v_ashrrev_i32_e32 v93, 31, v92
	s_cbranch_vccnz .LBB0_32
	v_readlane_b32 s16, v246, 6
	s_mov_b32 s0, 0xfff0
	v_readlane_b32 s17, v246, 7
	v_readlane_b32 s21, v246, 11
	v_add_u32_e32 v88, 0xffff0010, v120
	v_cmp_gt_i32_e32 vcc, s0, v120
	v_readlane_b32 s20, v246, 10
	v_mov_b32_e32 v90, s21
	v_mov_b32_e32 v91, s17
	v_cndmask_b32_e32 v89, 0, v93, vcc
	v_cndmask_b32_e32 v88, v88, v92, vcc
	v_cndmask_b32_e32 v91, v90, v91, vcc
	v_mov_b32_e32 v90, s20
	v_mov_b32_e32 v94, s16
	v_cndmask_b32_e32 v90, v90, v94, vcc
	v_lshlrev_b64 v[88:89], 12, v[88:89]
	v_lshl_add_u64 v[88:89], v[90:91], 0, v[88:89]
	v_lshlrev_b32_e32 v176, 4, v122
	v_lshl_add_u64 v[88:89], v[88:89], 0, v[176:177]
	global_load_dwordx4 v[104:107], v[88:89], off offset:16
	global_load_dwordx4 v[96:99], v[88:89], off
	global_load_dwordx4 v[100:103], v[88:89], off offset:2064
	s_nop 0
	global_load_dwordx4 v[88:91], v[88:89], off offset:2048
	s_mov_b64 s[8:9], 0
	v_readlane_b32 s18, v246, 8
	v_readlane_b32 s19, v246, 9
	v_readlane_b32 s22, v246, 12
	v_readlane_b32 s23, v246, 13
	v_readlane_b32 s24, v246, 14
	v_readlane_b32 s25, v246, 15
	v_readlane_b32 s26, v246, 16
	v_readlane_b32 s27, v246, 17
	v_readlane_b32 s28, v246, 18
	v_readlane_b32 s29, v246, 19
	v_readlane_b32 s30, v246, 20
	v_readlane_b32 s31, v246, 21
.LBB0_32:
	v_mov_b64_e32 v[118:119], v[54:55]
	v_mov_b64_e32 v[114:115], v[50:51]
	s_andn2_b64 vcc, exec, s[8:9]
	v_mov_b64_e32 v[116:117], v[52:53]
	v_mov_b64_e32 v[112:113], v[48:49]
	s_cbranch_vccnz .LBB0_34
	s_nop 0
	v_lshlrev_b64 v[88:89], 11, v[92:93]
	v_lshl_add_u64 v[88:89], v[124:125], 0, v[88:89]
	global_load_dwordx4 v[112:115], v[88:89], off
	global_load_dwordx4 v[116:119], v[88:89], off offset:1024
	v_mov_b64_e32 v[88:89], v[40:41]
	v_mov_b64_e32 v[90:91], v[42:43]
	v_mov_b64_e32 v[100:101], v[44:45]
	v_mov_b64_e32 v[102:103], v[46:47]
	v_mov_b64_e32 v[96:97], v[32:33]
	v_mov_b64_e32 v[98:99], v[34:35]
	v_mov_b64_e32 v[104:105], v[36:37]
	v_mov_b64_e32 v[106:107], v[38:39]

; __device__ __forceinline__ void norm_phase(const NormCfg& cf, int wvi) {
;     ...
;     for (int i = 0; i < 2; ++i) {
;       if (src32) {
;         xv[i][0] = Q0.xn[i][0].x; xv[i][1] = Q0.xn[i][0].y; xv[i][2] = Q0.xn[i][0].z; xv[i][3] = Q0.xn[i][0].w;
;         xv[i][4] = Q0.xn[i][1].x; xv[i][5] = Q0.xn[i][1].y; xv[i][6] = Q0.xn[i][1].z; xv[i][7] = Q0.xn[i][1].w;
;       } else unpack8(Q0.xb[i], xv[i]);
;       unpack8(Q0.yn[i], yv[i]);
;     }
;     ...
;     if (has_pre) {
;       float ss = 0.f;
; #pragma unroll
;       for (int i = 0; i < 2; ++i)
; #pragma unroll
;         for (int k = 0; k < 8; ++k) ss += xv[i][k] * xv[i][k];
;       ss = wave_sum(ss);
;       const float rstd = rsqrtf(ss * (1.f / DM) + EPS);
;       u32x4* hp = reinterpret_cast<u32x4*>(cf.h + (size_t)row * DM);
; #pragma unroll
;       for (int i = 0; i < 2; ++i) {
;         float hv[8];
; #pragma unroll
;         for (int k = 0; k < 8; ++k) hv[k] = xv[i][k] * rstd * gpr[i][k] * (1.f + sc[i][k]) + sh[i][k];
;         hp[lane + 64 * i] = pack8(hv);
;       }
;     }
.LBB0_39:
	s_waitcnt vmcnt(0)
	v_mov_b32_e32 v121, v108
.LBB0_40:
	s_or_b64 exec, exec, s[2:3]
	s_and_b64 vcc, exec, s[4:5]
	s_cbranch_vccnz .LBB0_26
	v_pk_mul_f32 v[92:93], v[24:25], v[24:25]
	v_pk_mul_f32 v[94:95], v[26:27], v[26:27]
	v_add_f32_e32 v92, v93, v92
	v_add_f32_e32 v92, v94, v92
	v_pk_mul_f32 v[108:109], v[20:21], v[20:21]
	v_add_f32_e32 v92, v95, v92
	v_add_f32_e32 v92, v108, v92
	v_pk_mul_f32 v[110:111], v[22:23], v[22:23]
	v_add_f32_e32 v92, v109, v92
	v_add_f32_e32 v92, v110, v92
	v_pk_mul_f32 v[130:131], v[28:29], v[28:29]
	v_add_f32_e32 v92, v111, v92
	v_add_f32_e32 v92, v92, v130
	v_pk_mul_f32 v[132:133], v[30:31], v[30:31]
	v_add_f32_e32 v92, v131, v92
	v_add_f32_e32 v92, v132, v92
	v_pk_mul_f32 v[134:135], v[16:17], v[16:17]
	v_add_f32_e32 v92, v133, v92
	v_add_f32_e32 v92, v134, v92
	v_pk_mul_f32 v[136:137], v[18:19], v[18:19]
	v_add_f32_e32 v92, v135, v92
	v_mbcnt_lo_u32_b32 v93, -1, 0
	v_mbcnt_hi_u32_b32 v93, -1, v93
	v_add_f32_e32 v92, v136, v92
	v_lshlrev_b32_e32 v93, 2, v93
	v_add_f32_e32 v92, v137, v92
	v_xor_b32_e32 v94, 0x80, v93
	ds_bpermute_b32 v94, v94, v92
	v_xor_b32_e32 v95, 8, v93
	s_mov_b32 s0, 0x800000
	s_nop 0
	v_pk_add_f32 v[108:109], v[64:65], 1.0 op_sel_hi:[1,0]
	v_pk_add_f32 v[110:111], v[66:67], 1.0 op_sel_hi:[1,0]
	s_waitcnt lgkmcnt(0)
	v_add_f32_e32 v92, v92, v94
	v_xor_b32_e32 v94, 64, v93
	ds_bpermute_b32 v94, v94, v92
	s_waitcnt lgkmcnt(0)
	v_add_f32_e32 v92, v92, v94
	v_xor_b32_e32 v94, 32, v93
	ds_bpermute_b32 v94, v94, v92
	s_waitcnt lgkmcnt(0)
	v_add_f32_e32 v92, v92, v94
	v_xor_b32_e32 v94, 16, v93
	ds_bpermute_b32 v94, v94, v92
	v_xor_b32_e32 v93, 4, v93
	s_waitcnt lgkmcnt(0)
	v_add_f32_e32 v92, v92, v94
	ds_bpermute_b32 v94, v95, v92
	s_waitcnt lgkmcnt(0)
	v_add_f32_e32 v94, v92, v94
	ds_bpermute_b32 v95, v93, v94
	s_nop 0
	v_pk_add_f32 v[92:93], v[72:73], 1.0 op_sel_hi:[1,0]
	s_waitcnt lgkmcnt(0)
	v_add_f32_e32 v94, v94, v95
	v_fmamk_f32 v94, v94, 0x3a800000, v192
	v_mul_f32_e32 v95, 0x4b800000, v94
	v_cmp_gt_f32_e32 vcc, s0, v94
	s_nop 1
	v_cndmask_b32_e32 v94, v94, v95, vcc
	v_rsq_f32_e32 v129, v94
	v_pk_add_f32 v[94:95], v[74:75], 1.0 op_sel_hi:[1,0]
	v_mul_f32_e32 v130, 0x45800000, v129
	v_cndmask_b32_e32 v130, v129, v130, vcc
	v_pk_mul_f32 v[24:25], v[24:25], v[130:131] op_sel_hi:[1,0]
	v_pk_mul_f32 v[20:21], v[20:21], v[130:131] op_sel_hi:[1,0]
	v_pk_mul_f32 v[26:27], v[26:27], v[130:131] op_sel_hi:[1,0]
	v_pk_mul_f32 v[22:23], v[22:23], v[130:131] op_sel_hi:[1,0]
	v_pk_mul_f32 v[24:25], v[8:9], v[24:25]
	v_pk_mul_f32 v[20:21], v[4:5], v[20:21]
	v_pk_mul_f32 v[26:27], v[10:11], v[26:27]
	v_pk_fma_f32 v[24:25], v[92:93], v[24:25], v[60:61]
	v_pk_fma_f32 v[92:93], v[108:109], v[20:21], v[56:57]
	v_pk_mul_f32 v[20:21], v[6:7], v[22:23]
	v_pk_fma_f32 v[26:27], v[94:95], v[26:27], v[62:63]
	v_pk_fma_f32 v[94:95], v[110:111], v[20:21], v[58:59]
	v_cvt_pk_bf16_f32 v20, v24, v25
	v_cvt_pk_bf16_f32 v21, v26, v27
	v_cvt_pk_bf16_f32 v22, v92, v93
	v_cvt_pk_bf16_f32 v23, v94, v95
	global_store_dwordx4 v[126:127], v[20:23], off offset:-1024
	v_pk_mul_f32 v[24:25], v[30:31], v[130:131] op_sel_hi:[1,0]
	v_pk_mul_f32 v[16:17], v[16:17], v[130:131] op_sel_hi:[1,0]
	v_pk_mul_f32 v[22:23], v[28:29], v[130:131] op_sel_hi:[1,0]
	v_pk_add_f32 v[20:21], v[84:85], 1.0 op_sel_hi:[1,0]
	v_pk_mul_f32 v[22:23], v[12:13], v[22:23]
	v_pk_mul_f32 v[24:25], v[14:15], v[24:25]
	v_pk_fma_f32 v[20:21], v[20:21], v[22:23], v[76:77]
	v_pk_add_f32 v[22:23], v[86:87], 1.0 op_sel_hi:[1,0]
	v_pk_mul_f32 v[16:17], v[0:1], v[16:17]
	v_pk_fma_f32 v[22:23], v[22:23], v[24:25], v[78:79]
	v_pk_add_f32 v[24:25], v[80:81], 1.0 op_sel_hi:[1,0]
	v_pk_mul_f32 v[18:19], v[18:19], v[130:131] op_sel_hi:[1,0]
	v_pk_fma_f32 v[24:25], v[24:25], v[16:17], v[68:69]
	v_pk_add_f32 v[16:17], v[82:83], 1.0 op_sel_hi:[1,0]
	v_pk_mul_f32 v[18:19], v[2:3], v[18:19]
	s_nop 0
	v_pk_fma_f32 v[26:27], v[16:17], v[18:19], v[70:71]
	v_cvt_pk_bf16_f32 v16, v20, v21
	v_cvt_pk_bf16_f32 v17, v22, v23
	v_cvt_pk_bf16_f32 v18, v24, v25
	v_cvt_pk_bf16_f32 v19, v26, v27
	global_store_dwordx4 v[126:127], v[16:19], off
	s_branch .LBB0_26
.LBB0_42:
	s_nop 0
	v_lshlrev_b32_e32 v24, 16, v108
	v_and_b32_e32 v25, 0xffff0000, v108
	v_lshlrev_b32_e32 v26, 16, v109
	v_and_b32_e32 v27, 0xffff0000, v109
	v_lshlrev_b32_e32 v20, 16, v110
	v_and_b32_e32 v21, 0xffff0000, v110
	v_lshlrev_b32_e32 v22, 16, v111
	v_and_b32_e32 v23, 0xffff0000, v111
	s_and_b64 vcc, exec, s[8:9]
	s_cbranch_vccnz .LBB0_29
.LBB0_43:
	s_nop 0
	v_lshlrev_b32_e32 v28, 16, v92
	v_and_b32_e32 v29, 0xffff0000, v92
	v_lshlrev_b32_e32 v30, 16, v93
	v_and_b32_e32 v31, 0xffff0000, v93
	v_lshlrev_b32_e32 v16, 16, v94
	v_and_b32_e32 v17, 0xffff0000, v94
	v_lshlrev_b32_e32 v18, 16, v95
	v_and_b32_e32 v19, 0xffff0000, v95
	s_branch .LBB0_29

; __device__ __forceinline__ float silu_f(float x) { return x * __builtin_amdgcn_rcpf(1.f + __expf(-x)); }
; __device__ __forceinline__ void ssd_combine_tokens(const Params& p, int l, int rows, int wvi) {
;     ...
;   for (int tok = r0; tok < r1; ++tok) {
;     float yf[8], yb[8], xs[8], zz[8], v[8];
;     unpack8(nyf, yf); unpack8(nyb, yb); unpack8(nxs, xs); unpack8(nzz, zz);
;     if (tok + 1 < r1) fetch(tok + 1);
;     float ss = 0.f;
; #pragma unroll
;     for (int i = 0; i < 8; ++i) { v[i] = (yf[i] + yb[i] + Dv * xs[i]) * silu_f(zz[i]); ss += v[i] * v[i]; }
;     ss = wave_sum(ss);
;     const float rstd = rsqrtf(ss * (1.f / 512.f) + EPS);
; #pragma unroll
;     for (int i = 0; i < 8; ++i) v[i] *= rstd * gn[i];
;     *reinterpret_cast<u32x4*>(p.bufA + (size_t)tok * DM + 256 + ch) = pack8(v);
;   }
.LBB0_439:
	s_or_b64 exec, exec, s[4:5]
	v_lshlrev_b32_e32 v66, 16, v24
	v_and_b32_e32 v67, 0xffff0000, v24
	v_mul_f32_e32 v43, 0xbfb8aa3b, v66
	v_exp_f32_e32 v43, v43
	v_mul_f32_e32 v53, 0xbfb8aa3b, v67
	v_exp_f32_e32 v53, v53
	v_lshlrev_b32_e32 v24, 16, v25
	v_add_f32_e32 v43, 1.0, v43
	v_and_b32_e32 v25, 0xffff0000, v25
	v_rcp_f32_e32 v70, v43
	v_add_f32_e32 v43, 1.0, v53
	v_mul_f32_e32 v53, 0xbfb8aa3b, v24
	v_exp_f32_e32 v53, v53
	v_mul_f32_e32 v71, 0xbfb8aa3b, v25
	v_exp_f32_e32 v73, v71
	v_lshlrev_b32_e32 v68, 16, v26
	v_and_b32_e32 v69, 0xffff0000, v26
	v_rcp_f32_e32 v71, v43
	v_add_f32_e32 v43, 1.0, v53
	v_mul_f32_e32 v53, 0xbfb8aa3b, v68
	v_rcp_f32_e32 v72, v43
	v_add_f32_e32 v43, 1.0, v73
	v_exp_f32_e32 v53, v53
	v_mul_f32_e32 v73, 0xbfb8aa3b, v69
	v_exp_f32_e32 v75, v73
	v_lshlrev_b32_e32 v26, 16, v27
	v_and_b32_e32 v27, 0xffff0000, v27
	v_rcp_f32_e32 v73, v43
	v_add_f32_e32 v43, 1.0, v53
	v_mul_f32_e32 v53, 0xbfb8aa3b, v26
	v_rcp_f32_e32 v74, v43
	v_add_f32_e32 v43, 1.0, v75
	v_exp_f32_e32 v53, v53
	v_mul_f32_e32 v75, 0xbfb8aa3b, v27
	v_exp_f32_e32 v77, v75
	v_lshlrev_b32_e32 v54, 16, v36
	v_and_b32_e32 v55, 0xffff0000, v36
	v_lshlrev_b32_e32 v36, 16, v37
	v_and_b32_e32 v37, 0xffff0000, v37
	v_lshlrev_b32_e32 v58, 16, v32
	v_and_b32_e32 v59, 0xffff0000, v32
	v_lshlrev_b32_e32 v32, 16, v33
	v_and_b32_e32 v33, 0xffff0000, v33
	v_lshlrev_b32_e32 v62, 16, v28
	v_and_b32_e32 v63, 0xffff0000, v28
	v_lshlrev_b32_e32 v28, 16, v29
	v_and_b32_e32 v29, 0xffff0000, v29
	v_pk_add_f32 v[32:33], v[36:37], v[32:33]
	v_rcp_f32_e32 v75, v43
	v_add_f32_e32 v43, 1.0, v53
	v_pk_fma_f32 v[28:29], v[40:41], v[28:29], v[32:33]
	v_pk_add_f32 v[32:33], v[54:55], v[58:59]
	v_lshlrev_b32_e32 v56, 16, v38
	v_and_b32_e32 v57, 0xffff0000, v38
	v_lshlrev_b32_e32 v38, 16, v39
	v_and_b32_e32 v39, 0xffff0000, v39
	v_lshlrev_b32_e32 v60, 16, v34
	v_and_b32_e32 v61, 0xffff0000, v34
	v_lshlrev_b32_e32 v34, 16, v35
	v_and_b32_e32 v35, 0xffff0000, v35
	v_rcp_f32_e32 v76, v43
	v_add_f32_e32 v43, 1.0, v77
	v_pk_fma_f32 v[32:33], v[40:41], v[62:63], v[32:33]
	v_pk_mul_f32 v[36:37], v[70:71], v[66:67]
	v_lshlrev_b32_e32 v64, 16, v30
	v_and_b32_e32 v65, 0xffff0000, v30
	v_lshlrev_b32_e32 v30, 16, v31
	v_and_b32_e32 v31, 0xffff0000, v31
	v_rcp_f32_e32 v77, v43
	v_pk_add_f32 v[34:35], v[38:39], v[34:35]
	v_pk_mul_f32 v[24:25], v[72:73], v[24:25]
	v_pk_mul_f32 v[32:33], v[32:33], v[36:37]
	v_pk_fma_f32 v[30:31], v[40:41], v[30:31], v[34:35]
	v_pk_add_f32 v[34:35], v[56:57], v[60:61]
	v_pk_mul_f32 v[24:25], v[28:29], v[24:25]
	v_pk_mul_f32 v[36:37], v[32:33], v[32:33]
	v_pk_fma_f32 v[34:35], v[40:41], v[64:65], v[34:35]
	v_pk_mul_f32 v[38:39], v[74:75], v[68:69]
	v_pk_mul_f32 v[28:29], v[24:25], v[24:25]
	v_add_f32_e32 v36, v36, v37
	v_pk_mul_f32 v[34:35], v[34:35], v[38:39]
	v_add_f32_e32 v28, v28, v36
	v_pk_mul_f32 v[26:27], v[76:77], v[26:27]
	v_pk_mul_f32 v[38:39], v[34:35], v[34:35]
	v_add_f32_e32 v28, v29, v28
	v_pk_mul_f32 v[26:27], v[30:31], v[26:27]
	v_add_f32_e32 v28, v38, v28
	v_mbcnt_lo_u32_b32 v43, -1, 0
	v_mbcnt_hi_u32_b32 v43, -1, v43
	v_pk_mul_f32 v[30:31], v[26:27], v[26:27]
	v_add_f32_e32 v28, v39, v28
	v_lshlrev_b32_e32 v43, 2, v43
	v_add_f32_e32 v28, v30, v28
	v_xor_b32_e32 v53, 0x80, v43
	v_add_f32_e32 v28, v31, v28
	ds_bpermute_b32 v29, v53, v28
	v_xor_b32_e32 v30, 64, v43
	s_mov_b32 s0, 0x800000
	s_nop 0
	s_waitcnt lgkmcnt(0)
	v_add_f32_e32 v28, v28, v29
	ds_bpermute_b32 v29, v30, v28
	v_xor_b32_e32 v30, 32, v43
	s_waitcnt lgkmcnt(0)
	v_add_f32_e32 v28, v28, v29
	ds_bpermute_b32 v29, v30, v28
	v_xor_b32_e32 v30, 16, v43
	s_waitcnt lgkmcnt(0)
	v_add_f32_e32 v28, v28, v29
	ds_bpermute_b32 v29, v30, v28
	v_xor_b32_e32 v30, 8, v43
	s_waitcnt lgkmcnt(0)
	v_add_f32_e32 v28, v28, v29
	ds_bpermute_b32 v29, v30, v28
	v_xor_b32_e32 v30, 4, v43
	s_waitcnt lgkmcnt(0)
	v_add_f32_e32 v28, v28, v29
	ds_bpermute_b32 v29, v30, v28
	s_waitcnt lgkmcnt(0)
	v_add_f32_e32 v28, v28, v29
	v_fmamk_f32 v28, v28, 0x3b000000, v192
	v_mul_f32_e32 v29, 0x4b800000, v28
	v_cmp_gt_f32_e32 vcc, s0, v28
	s_mov_b64 s[0:1], 0x800
	v_lshl_add_u64 v[48:49], v[48:49], 0, s[0:1]
	v_cndmask_b32_e32 v28, v28, v29, vcc
	v_rsq_f32_e32 v28, v28
	s_nop 0
	v_mul_f32_e32 v29, 0x45800000, v28
	v_cndmask_b32_e32 v28, v28, v29, vcc
	v_pk_mul_f32 v[30:31], v[4:5], v[28:29] op_sel_hi:[1,0]
	s_nop 0
	v_pk_mul_f32 v[30:31], v[32:33], v[30:31]
	v_pk_mul_f32 v[32:33], v[6:7], v[28:29] op_sel_hi:[1,0]
	s_nop 0
	v_pk_mul_f32 v[32:33], v[24:25], v[32:33]
	v_pk_mul_f32 v[24:25], v[0:1], v[28:29] op_sel_hi:[1,0]
	s_nop 0
	v_pk_mul_f32 v[34:35], v[34:35], v[24:25]
	v_pk_mul_f32 v[24:25], v[2:3], v[28:29] op_sel_hi:[1,0]
	s_nop 0
	v_pk_mul_f32 v[28:29], v[26:27], v[24:25]
	v_cvt_pk_bf16_f32 v24, v30, v31
	v_cvt_pk_bf16_f32 v25, v32, v33
	v_cvt_pk_bf16_f32 v26, v34, v35
	v_cvt_pk_bf16_f32 v27, v28, v29
	v_lshl_add_u64 v[28:29], v[46:47], 0, v[176:177]
	global_store_dwordx4 v[28:29], v[24:27], off
	v_lshl_add_u64 v[46:47], v[46:47], 0, s[0:1]
	s_mov_b64 s[0:1], 0x400
	s_waitcnt vmcnt(1)
	v_mov_b64_e32 v[38:39], v[10:11]
	v_mov_b64_e32 v[36:37], v[8:9]
	v_mov_b64_e32 v[26:27], v[22:23]
	v_mov_b64_e32 v[34:35], v[14:15]
	v_mov_b64_e32 v[30:31], v[18:19]
	v_lshl_add_u64 v[44:45], v[44:45], 0, s[0:1]
	v_lshl_add_u64 v[50:51], v[50:51], 0, s[0:1]
	v_mov_b64_e32 v[24:25], v[20:21]
	v_mov_b64_e32 v[32:33], v[12:13]
	v_mov_b64_e32 v[28:29], v[16:17]
	s_andn2_b64 exec, exec, s[6:7]
	s_cbranch_execz .LBB0_442

; __device__ __forceinline__ void norm_phase(const NormCfg& cf, int wvi) {
;     ...
;   float gpo[2][8], gpr[2][8], gate[2][8], sh[2][8], sc[2][8];
; #pragma unroll
;   for (int i = 0; i < 2; ++i) {
; #pragma unroll
;     for (int k = 0; k < 8; ++k) { gpo[i][k] = 0.f; gpr[i][k] = 0.f; gate[i][k] = 0.f; sh[i][k] = 0.f; sc[i][k] = 0.f; }
;     if (has_post) ld8(cf.g_post, i, gpo[i]);
;     if (has_pre) ld8(cf.g_pre, i, gpr[i]);
;   }
;   int cur_m = -1;
;   struct RowRegs { float4 xn[2][2]; u32x4 xb[2], yn[2]; };
;   RowRegs Q0, Q1;
;   auto fetch = [&](int row, RowRegs& Q) {
;     if (src32) {
;       const float* src = (row < TL) ? cf.src_lat + (size_t)row * DM : cf.src_ctx + (size_t)(row - TL) * DM;
; #pragma unroll
;       for (int i = 0; i < 2; ++i) {
;         Q.xn[i][0] = reinterpret_cast<const float4*>(src)[2 * (lane + 64 * i)];
;         Q.xn[i][1] = reinterpret_cast<const float4*>(src)[2 * (lane + 64 * i) + 1];
;       }
;     } else {
;       const u32x4* xp = reinterpret_cast<const u32x4*>(cf.xs + (size_t)row * DM);
; #pragma unroll
;       for (int i = 0; i < 2; ++i) Q.xb[i] = xp[lane + 64 * i];
;     }
;     if (has_post) {
;       const u32x4* yp = reinterpret_cast<const u32x4*>(cf.y + (size_t)row * DM);
; #pragma unroll
;       for (int i = 0; i < 2; ++i) Q.yn[i] = yp[lane + 64 * i];
;     }
;   };
;   fetch(r0, Q0);
;   if (r0 + 8 < r1) fetch(r0 + 8, Q1);
;   for (int row = r0; row < r1; row += 8) {
;     float xv[2][8], yv[2][8];
; #pragma unroll
;     for (int i = 0; i < 2; ++i) {
;       if (src32) {
;         xv[i][0] = Q0.xn[i][0].x; xv[i][1] = Q0.xn[i][0].y; xv[i][2] = Q0.xn[i][0].z; xv[i][3] = Q0.xn[i][0].w;
;         xv[i][4] = Q0.xn[i][1].x; xv[i][5] = Q0.xn[i][1].y; xv[i][6] = Q0.xn[i][1].z; xv[i][7] = Q0.xn[i][1].w;
;       } else unpack8(Q0.xb[i], xv[i]);
;       unpack8(Q0.yn[i], yv[i]);
;     }
;     Q0 = Q1;
;     if (row + 16 < r1) fetch(row + 16, Q1);
.LBB0_1002:
	s_or_b64 exec, exec, s[2:3]
	v_readlane_b32 s0, v246, 24
	v_readlane_b32 s1, v246, 25
	v_lshlrev_b64 v[88:89], 11, v[88:89]
	v_readlane_b32 s36, v246, 63
	v_lshl_add_u64 v[182:183], s[0:1], 0, v[176:177]
	s_mov_b32 s0, 0xffff0010
	v_add3_u32 v214, v93, v92, s0
	v_readlane_b32 s0, v247, 63
	v_or_b32_e32 v88, v88, v176
	v_readlane_b32 s1, v246, 0
	v_readlane_b32 s46, v245, 9
	v_readlane_b32 s47, v245, 10
	v_lshl_add_u64 v[186:187], s[0:1], 0, v[88:89]
	v_readlane_b32 s0, v246, 28
	v_or_b32_e32 v90, 0x80, v180
	v_lshl_add_u64 v[184:185], s[46:47], 0, v[176:177]
	v_readlane_b32 s1, v246, 29
	v_mov_b32_e32 v176, v177
	v_mov_b32_e32 v191, -1
	v_lshl_add_u64 v[188:189], s[0:1], 0, v[88:89]
	s_mov_b64 s[12:13], 0
	v_lshlrev_b32_e32 v190, 4, v90
	v_mov_b64_e32 v[90:91], v[176:177]
	v_mov_b64_e32 v[98:99], v[176:177]
	v_mov_b64_e32 v[88:89], v[176:177]
	v_mov_b64_e32 v[96:97], v[176:177]
	v_mov_b64_e32 v[94:95], v[176:177]
	v_mov_b64_e32 v[106:107], v[176:177]
	v_mov_b64_e32 v[92:93], v[176:177]
	v_mov_b64_e32 v[104:105], v[176:177]
	v_mov_b64_e32 v[102:103], v[176:177]
	v_mov_b64_e32 v[118:119], v[176:177]
	v_mov_b64_e32 v[100:101], v[176:177]
	v_mov_b64_e32 v[116:117], v[176:177]
	v_mov_b64_e32 v[110:111], v[176:177]
	v_mov_b64_e32 v[134:135], v[176:177]
	v_mov_b64_e32 v[108:109], v[176:177]
	v_mov_b64_e32 v[132:133], v[176:177]
	v_mov_b64_e32 v[114:115], v[176:177]
	v_mov_b64_e32 v[112:113], v[176:177]
	v_mov_b64_e32 v[122:123], v[176:177]
	v_mov_b64_e32 v[120:121], v[176:177]
	v_mov_b64_e32 v[126:127], v[176:177]
	v_mov_b64_e32 v[124:125], v[176:177]
	v_mov_b64_e32 v[130:131], v[176:177]
	v_mov_b64_e32 v[128:129], v[176:177]
	v_readlane_b32 s2, v246, 26
	v_readlane_b32 s3, v246, 27
	v_readlane_b32 s37, v245, 0
	v_readlane_b32 s38, v245, 1
	v_readlane_b32 s39, v245, 2
	v_readlane_b32 s40, v245, 3
	v_readlane_b32 s41, v245, 4
	v_readlane_b32 s42, v245, 5
	v_readlane_b32 s43, v245, 6
	v_readlane_b32 s44, v245, 7
	v_readlane_b32 s45, v245, 8
	v_readlane_b32 s48, v245, 11
	v_readlane_b32 s49, v245, 12
	v_readlane_b32 s50, v245, 13
	v_readlane_b32 s51, v245, 14
	s_waitcnt vmcnt(0)
	s_branch .LBB0_1004
.LBB0_1003:
	s_nop 0
	v_add_u32_e32 v33, 0xfff8, v214
	v_mov_b64_e32 v[86:87], v[74:75]
	v_mov_b64_e32 v[82:83], v[78:79]
	v_mov_b64_e32 v[170:171], v[70:71]
	v_mov_b64_e32 v[174:175], v[66:67]
	v_add_u32_e32 v32, 8, v214
	v_cmp_ge_i32_e32 vcc, v33, v213
	v_mov_b64_e32 v[84:85], v[72:73]
	v_mov_b64_e32 v[80:81], v[76:77]
	v_mov_b64_e32 v[168:169], v[68:69]
	v_mov_b64_e32 v[172:173], v[64:65]
	s_waitcnt vmcnt(4)
	v_mov_b64_e32 v[72:73], v[160:161]
	v_mov_b64_e32 v[76:77], v[164:165]
	v_mov_b64_e32 v[68:69], v[156:157]
	v_mov_b64_e32 v[64:65], v[152:153]
	v_lshl_add_u64 v[186:187], v[186:187], 0, s[84:85]
	v_lshl_add_u64 v[188:189], v[188:189], 0, s[84:85]
	s_or_b64 s[12:13], vcc, s[12:13]
	v_mov_b32_e32 v214, v32
	v_mov_b64_e32 v[74:75], v[162:163]
	v_mov_b64_e32 v[78:79], v[166:167]
	v_mov_b64_e32 v[70:71], v[158:159]
	v_mov_b64_e32 v[66:67], v[154:155]
	v_mov_b64_e32 v[38:39], v[54:55]
	v_mov_b64_e32 v[54:55], v[150:151]
	v_mov_b64_e32 v[36:37], v[52:53]
	v_mov_b64_e32 v[52:53], v[148:149]
	v_mov_b64_e32 v[34:35], v[50:51]
	v_mov_b64_e32 v[50:51], v[142:143]
	v_mov_b64_e32 v[32:33], v[48:49]
	v_mov_b64_e32 v[48:49], v[140:141]
	v_mov_b64_e32 v[42:43], v[62:63]
	v_mov_b64_e32 v[62:63], v[146:147]
	v_mov_b64_e32 v[40:41], v[60:61]
	v_mov_b64_e32 v[60:61], v[144:145]
	v_mov_b64_e32 v[46:47], v[58:59]
	v_mov_b64_e32 v[58:59], v[138:139]
	v_mov_b64_e32 v[44:45], v[56:57]
	v_mov_b64_e32 v[56:57], v[136:137]
	s_andn2_b64 exec, exec, s[12:13]
	s_cbranch_execz .LBB0_1029

; __device__ __forceinline__ void norm_phase(const NormCfg& cf, int wvi) {
;     ...
;   auto fetch = [&](int row, RowRegs& Q) {
;     if (src32) {
;       const float* src = (row < TL) ? cf.src_lat + (size_t)row * DM : cf.src_ctx + (size_t)(row - TL) * DM;
; #pragma unroll
;       for (int i = 0; i < 2; ++i) {
;         Q.xn[i][0] = reinterpret_cast<const float4*>(src)[2 * (lane + 64 * i)];
;         Q.xn[i][1] = reinterpret_cast<const float4*>(src)[2 * (lane + 64 * i) + 1];
;       }
;     } else {
;       const u32x4* xp = reinterpret_cast<const u32x4*>(cf.xs + (size_t)row * DM);
; #pragma unroll
;       for (int i = 0; i < 2; ++i) Q.xb[i] = xp[lane + 64 * i];
;     }
;     if (has_post) {
;       const u32x4* yp = reinterpret_cast<const u32x4*>(cf.y + (size_t)row * DM);
; #pragma unroll
;       for (int i = 0; i < 2; ++i) Q.yn[i] = yp[lane + 64 * i];
;     }
;   };
;   fetch(r0, Q0);
;   if (r0 + 8 < r1) fetch(r0 + 8, Q1);
;   for (int row = r0; row < r1; row += 8) {
;     float xv[2][8], yv[2][8];
; #pragma unroll
;     for (int i = 0; i < 2; ++i) {
;       if (src32) {
;         xv[i][0] = Q0.xn[i][0].x; xv[i][1] = Q0.xn[i][0].y; xv[i][2] = Q0.xn[i][0].z; xv[i][3] = Q0.xn[i][0].w;
;         xv[i][4] = Q0.xn[i][1].x; xv[i][5] = Q0.xn[i][1].y; xv[i][6] = Q0.xn[i][1].z; xv[i][7] = Q0.xn[i][1].w;
;       } else unpack8(Q0.xb[i], xv[i]);
;       unpack8(Q0.yn[i], yv[i]);
;     }
;     Q0 = Q1;
;     if (row + 16 < r1) fetch(row + 16, Q1);
.LBB0_1006:
	s_nop 0
	v_add_u32_e32 v168, 0x10000, v214
	v_mov_b64_e32 v[162:163], v[74:75]
	v_mov_b64_e32 v[166:167], v[78:79]
	v_mov_b64_e32 v[158:159], v[70:71]
	v_mov_b64_e32 v[154:155], v[66:67]
	v_add_u32_e32 v170, 0xfff0, v214
	v_cmp_lt_i32_e32 vcc, v168, v213
	v_mov_b64_e32 v[136:137], v[56:57]
	v_mov_b64_e32 v[138:139], v[58:59]
	v_mov_b64_e32 v[144:145], v[60:61]
	v_mov_b64_e32 v[146:147], v[62:63]
	v_mov_b64_e32 v[140:141], v[48:49]
	v_mov_b64_e32 v[142:143], v[50:51]
	v_mov_b64_e32 v[148:149], v[52:53]
	v_mov_b64_e32 v[150:151], v[54:55]
	v_mov_b64_e32 v[160:161], v[72:73]
	v_mov_b64_e32 v[164:165], v[76:77]
	v_mov_b64_e32 v[156:157], v[68:69]
	v_mov_b64_e32 v[152:153], v[64:65]
	s_and_saveexec_b64 s[2:3], vcc
	s_cbranch_execz .LBB0_1013
	s_mov_b64 s[10:11], -1
	s_and_b64 vcc, exec, s[8:9]
	v_ashrrev_i32_e32 v169, 31, v168
	s_cbranch_vccnz .LBB0_1009
	s_mov_b32 s0, 0xfff0
	v_cmp_gt_i32_e32 vcc, s0, v170
	v_mov_b32_e32 v138, s20
	v_mov_b32_e32 v139, s15
	v_cndmask_b32_e32 v137, 0, v169, vcc
	v_cndmask_b32_e32 v136, v214, v168, vcc
	v_cndmask_b32_e32 v139, v138, v139, vcc
	v_mov_b32_e32 v138, s21
	v_mov_b32_e32 v140, s14
	v_cndmask_b32_e32 v138, v138, v140, vcc
	v_lshlrev_b64 v[136:137], 12, v[136:137]
	v_lshl_add_u64 v[136:137], v[138:139], 0, v[136:137]
	v_lshlrev_b32_e32 v176, 4, v180
	v_lshl_add_u64 v[136:137], v[136:137], 0, v[176:177]
	global_load_dwordx4 v[148:151], v[136:137], off offset:16
	global_load_dwordx4 v[140:143], v[136:137], off
	global_load_dwordx4 v[144:147], v[136:137], off offset:2064
	s_nop 0
	global_load_dwordx4 v[136:139], v[136:137], off offset:2048
	s_mov_b64 s[10:11], 0
.LBB0_1009:
	v_mov_b64_e32 v[154:155], v[66:67]
	v_mov_b64_e32 v[158:159], v[70:71]
	s_andn2_b64 vcc, exec, s[10:11]
	v_mov_b64_e32 v[152:153], v[64:65]
	v_mov_b64_e32 v[156:157], v[68:69]
	s_cbranch_vccnz .LBB0_1011
	s_nop 0
	v_lshlrev_b64 v[136:137], 11, v[168:169]
	v_lshl_add_u64 v[136:137], v[182:183], 0, v[136:137]
	global_load_dwordx4 v[152:155], v[136:137], off
	global_load_dwordx4 v[156:159], v[136:137], off offset:1024
	v_mov_b64_e32 v[150:151], v[54:55]
	v_mov_b64_e32 v[148:149], v[52:53]
	v_mov_b64_e32 v[142:143], v[50:51]
	v_mov_b64_e32 v[140:141], v[48:49]
	v_mov_b64_e32 v[146:147], v[62:63]
	v_mov_b64_e32 v[144:145], v[60:61]
	v_mov_b64_e32 v[138:139], v[58:59]
	v_mov_b64_e32 v[136:137], v[56:57]

; __device__ __forceinline__ void norm_phase(const NormCfg& cf, int wvi) {
;     ...
;     const int mrow = (row < TL) ? (row >> 12) : 16;
;     if (mrow != cur_m) {
;       cur_m = mrow;
; #pragma unroll
;       for (int i = 0; i < 2; ++i) {
;         if (has_post) ld8(cf.mod_post + (size_t)mrow * MODROW + cf.gate_i * DM, i, gate[i]);
;         if (has_pre) {
;           ld8(cf.mod_pre + (size_t)mrow * MODROW + cf.shift_i * DM, i, sh[i]);
;           ld8(cf.mod_pre + (size_t)mrow * MODROW + (cf.shift_i + 1) * DM, i, sc[i]);
;         }
;       }
;     }
;     if (has_post) {
;       float ss = 0.f;
; #pragma unroll
;       for (int i = 0; i < 2; ++i)
; #pragma unroll
;         for (int k = 0; k < 8; ++k) ss += yv[i][k] * yv[i][k];
;       ss = wave_sum(ss);
;       const float rstd = rsqrtf(ss * (1.f / DM) + EPS) * cf.res_w;
; #pragma unroll
;       for (int i = 0; i < 2; ++i)
; #pragma unroll
;         for (int k = 0; k < 8; ++k) xv[i][k] += gate[i][k] * gpo[i][k] * yv[i][k] * rstd;
;       if (cf.out32) {
;         float4* op = reinterpret_cast<float4*>(cf.out32 + (size_t)row * DM);
; #pragma unroll
;         for (int i = 0; i < 2; ++i) {
;           op[2 * (lane + 64 * i)] = make_float4(xv[i][0], xv[i][1], xv[i][2], xv[i][3]);
;           op[2 * (lane + 64 * i) + 1] = make_float4(xv[i][4], xv[i][5], xv[i][6], xv[i][7]);
;         }
;       } else {
;         u32x4* xp = reinterpret_cast<u32x4*>(cf.xs + (size_t)row * DM);
; #pragma unroll
;         for (int i = 0; i < 2; ++i) {
;           const u32x4 pk = pack8(xv[i]);
;           xp[lane + 64 * i] = pk;
;           unpack8(pk, xv[i]);
;         }
;       }
;     }
.LBB0_1022:
	s_waitcnt vmcnt(0)
	v_mov_b32_e32 v191, v174
.LBB0_1023:
	s_or_b64 exec, exec, s[2:3]
	s_and_b64 vcc, exec, s[6:7]
	s_cbranch_vccnz .LBB0_1025
	v_lshlrev_b32_e32 v172, 16, v80
	v_and_b32_e32 v173, 0xffff0000, v80
	v_lshlrev_b32_e32 v80, 16, v81
	v_and_b32_e32 v81, 0xffff0000, v81
	v_pk_mul_f32 v[216:217], v[172:173], v[172:173]
	v_pk_mul_f32 v[218:219], v[80:81], v[80:81]
	v_add_f32_e32 v176, v216, v217
	v_lshlrev_b32_e32 v174, 16, v82
	v_and_b32_e32 v175, 0xffff0000, v82
	v_add_f32_e32 v176, v218, v176
	v_pk_mul_f32 v[220:221], v[174:175], v[174:175]
	v_add_f32_e32 v176, v219, v176
	v_lshlrev_b32_e32 v82, 16, v83
	v_and_b32_e32 v83, 0xffff0000, v83
	v_add_f32_e32 v176, v220, v176
	v_pk_mul_f32 v[222:223], v[82:83], v[82:83]
	v_add_f32_e32 v176, v221, v176
	v_lshlrev_b32_e32 v168, 16, v84
	v_and_b32_e32 v169, 0xffff0000, v84
	v_add_f32_e32 v176, v222, v176
	v_pk_mul_f32 v[224:225], v[168:169], v[168:169]
	v_add_f32_e32 v176, v223, v176
	v_lshlrev_b32_e32 v84, 16, v85
	v_and_b32_e32 v85, 0xffff0000, v85
	v_add_f32_e32 v176, v224, v176
	v_pk_mul_f32 v[226:227], v[84:85], v[84:85]
	v_add_f32_e32 v176, v225, v176
	v_lshlrev_b32_e32 v170, 16, v86
	v_and_b32_e32 v171, 0xffff0000, v86
	v_add_f32_e32 v176, v226, v176
	v_pk_mul_f32 v[228:229], v[170:171], v[170:171]
	v_add_f32_e32 v176, v227, v176
	v_lshlrev_b32_e32 v86, 16, v87
	v_and_b32_e32 v87, 0xffff0000, v87
	v_add_f32_e32 v176, v228, v176
	v_pk_mul_f32 v[230:231], v[86:87], v[86:87]
	v_add_f32_e32 v176, v229, v176
	v_mbcnt_lo_u32_b32 v215, -1, 0
	v_mbcnt_hi_u32_b32 v215, -1, v215
	v_add_f32_e32 v176, v230, v176
	v_lshlrev_b32_e32 v215, 2, v215
	v_add_f32_e32 v176, v231, v176
	v_xor_b32_e32 v216, 0x80, v215
	ds_bpermute_b32 v216, v216, v176
	s_mov_b32 s0, 0x800000
	s_waitcnt lgkmcnt(0)
	v_add_f32_e32 v176, v176, v216
	v_xor_b32_e32 v216, 64, v215
	ds_bpermute_b32 v216, v216, v176
	s_waitcnt lgkmcnt(0)
	v_add_f32_e32 v176, v176, v216
	v_xor_b32_e32 v216, 32, v215
	ds_bpermute_b32 v216, v216, v176
	s_waitcnt lgkmcnt(0)
	v_add_f32_e32 v176, v176, v216
	v_xor_b32_e32 v216, 16, v215
	ds_bpermute_b32 v216, v216, v176
	s_waitcnt lgkmcnt(0)
	v_add_f32_e32 v176, v176, v216
	v_xor_b32_e32 v216, 8, v215
	ds_bpermute_b32 v216, v216, v176
	v_xor_b32_e32 v215, 4, v215
	s_waitcnt lgkmcnt(0)
	v_add_f32_e32 v176, v176, v216
	ds_bpermute_b32 v215, v215, v176
	s_nop 0
	v_pk_mul_f32 v[216:217], v[8:9], v[120:121]
	s_waitcnt lgkmcnt(0)
	v_add_f32_e32 v176, v176, v215
	v_fmamk_f32 v176, v176, 0x3a800000, v192
	v_mul_f32_e32 v215, 0x4b800000, v176
	v_cmp_gt_f32_e32 vcc, s0, v176
	v_pk_mul_f32 v[172:173], v[216:217], v[172:173]
	s_nop 0
	v_cndmask_b32_e32 v176, v176, v215, vcc
	v_rsq_f32_e32 v176, v176
	s_nop 0
	v_mul_f32_e32 v215, 0x45800000, v176
	v_cndmask_b32_e32 v176, v176, v215, vcc
	v_mul_f32_e32 v176, 0.5, v176
	v_pk_fma_f32 v[32:33], v[172:173], v[176:177], v[32:33] op_sel_hi:[1,0,1]
	v_pk_mul_f32 v[172:173], v[10:11], v[122:123]
	s_nop 0
	v_pk_mul_f32 v[80:81], v[172:173], v[80:81]
	s_nop 0
	v_pk_fma_f32 v[34:35], v[80:81], v[176:177], v[34:35] op_sel_hi:[1,0,1]
	v_pk_mul_f32 v[80:81], v[4:5], v[112:113]
	s_nop 0
	v_pk_mul_f32 v[80:81], v[80:81], v[174:175]
	s_nop 0
	v_pk_fma_f32 v[80:81], v[80:81], v[176:177], v[36:37] op_sel_hi:[1,0,1]
	v_pk_mul_f32 v[36:37], v[6:7], v[114:115]
	s_nop 0
	v_pk_mul_f32 v[36:37], v[36:37], v[82:83]
	s_nop 0
	v_pk_fma_f32 v[82:83], v[36:37], v[176:177], v[38:39] op_sel_hi:[1,0,1]
	v_pk_mul_f32 v[36:37], v[24:25], v[128:129]
	v_cvt_pk_bf16_f32 v38, v80, v81
	v_pk_mul_f32 v[36:37], v[36:37], v[168:169]
	v_cvt_pk_bf16_f32 v39, v82, v83
	v_pk_fma_f32 v[44:45], v[36:37], v[176:177], v[44:45] op_sel_hi:[1,0,1]
	v_pk_mul_f32 v[36:37], v[26:27], v[130:131]
	s_nop 0
	v_pk_mul_f32 v[36:37], v[36:37], v[84:85]
	s_nop 0
	v_pk_fma_f32 v[46:47], v[36:37], v[176:177], v[46:47] op_sel_hi:[1,0,1]
	v_pk_mul_f32 v[36:37], v[20:21], v[124:125]
	s_nop 0
	v_pk_mul_f32 v[36:37], v[36:37], v[170:171]
	s_nop 0
	v_pk_fma_f32 v[84:85], v[36:37], v[176:177], v[40:41] op_sel_hi:[1,0,1]
	v_pk_mul_f32 v[36:37], v[22:23], v[126:127]
	v_cvt_pk_bf16_f32 v40, v44, v45
	v_pk_mul_f32 v[36:37], v[36:37], v[86:87]
	v_cvt_pk_bf16_f32 v41, v46, v47
	v_pk_fma_f32 v[86:87], v[36:37], v[176:177], v[42:43] op_sel_hi:[1,0,1]
	v_cvt_pk_bf16_f32 v36, v32, v33
	v_cvt_pk_bf16_f32 v37, v34, v35
	v_cvt_pk_bf16_f32 v42, v84, v85
	v_cvt_pk_bf16_f32 v43, v86, v87
	global_store_dwordx4 v[188:189], v[36:39], off offset:-1024
	v_lshlrev_b32_e32 v32, 16, v36
	v_and_b32_e32 v33, 0xffff0000, v36
	v_lshlrev_b32_e32 v34, 16, v37
	v_and_b32_e32 v35, 0xffff0000, v37
	v_lshlrev_b32_e32 v36, 16, v38
	v_and_b32_e32 v37, 0xffff0000, v38
	v_lshlrev_b32_e32 v38, 16, v39
	v_and_b32_e32 v39, 0xffff0000, v39
	global_store_dwordx4 v[188:189], v[40:43], off
	v_lshlrev_b32_e32 v44, 16, v40
	v_and_b32_e32 v45, 0xffff0000, v40
	v_lshlrev_b32_e32 v46, 16, v41
	v_and_b32_e32 v47, 0xffff0000, v41
	v_lshlrev_b32_e32 v40, 16, v42
	v_and_b32_e32 v41, 0xffff0000, v42
	v_lshlrev_b32_e32 v42, 16, v43
	v_and_b32_e32 v43, 0xffff0000, v43
; __device__ __forceinline__ void norm_phase(const NormCfg& cf, int wvi) {
;     ...
;     for (int i = 0; i < 2; ++i) {
;       if (src32) {
;         xv[i][0] = Q0.xn[i][0].x; xv[i][1] = Q0.xn[i][0].y; xv[i][2] = Q0.xn[i][0].z; xv[i][3] = Q0.xn[i][0].w;
;         xv[i][4] = Q0.xn[i][1].x; xv[i][5] = Q0.xn[i][1].y; xv[i][6] = Q0.xn[i][1].z; xv[i][7] = Q0.xn[i][1].w;
;       } else unpack8(Q0.xb[i], xv[i]);
;       unpack8(Q0.yn[i], yv[i]);
;     }
;     ...
;     if (has_pre) {
;       float ss = 0.f;
; #pragma unroll
;       for (int i = 0; i < 2; ++i)
; #pragma unroll
;         for (int k = 0; k < 8; ++k) ss += xv[i][k] * xv[i][k];
;       ss = wave_sum(ss);
;       const float rstd = rsqrtf(ss * (1.f / DM) + EPS);
;       u32x4* hp = reinterpret_cast<u32x4*>(cf.h + (size_t)row * DM);
; #pragma unroll
;       for (int i = 0; i < 2; ++i) {
;         float hv[8];
; #pragma unroll
;         for (int k = 0; k < 8; ++k) hv[k] = xv[i][k] * rstd * gpr[i][k] * (1.f + sc[i][k]) + sh[i][k];
;         hp[lane + 64 * i] = pack8(hv);
;       }
;     }
.LBB0_1025:
	s_and_b64 vcc, exec, s[4:5]
	s_cbranch_vccnz .LBB0_1003
	v_pk_mul_f32 v[80:81], v[32:33], v[32:33]
	v_pk_mul_f32 v[82:83], v[34:35], v[34:35]
	v_add_f32_e32 v80, v81, v80
	v_add_f32_e32 v80, v82, v80
	v_pk_mul_f32 v[84:85], v[36:37], v[36:37]
	v_add_f32_e32 v80, v83, v80
	v_add_f32_e32 v80, v84, v80
	v_pk_mul_f32 v[86:87], v[38:39], v[38:39]
	v_add_f32_e32 v80, v85, v80
	v_add_f32_e32 v80, v86, v80
	v_pk_mul_f32 v[168:169], v[44:45], v[44:45]
	v_add_f32_e32 v80, v87, v80
	v_add_f32_e32 v80, v168, v80
	v_pk_mul_f32 v[170:171], v[46:47], v[46:47]
	v_add_f32_e32 v80, v169, v80
	v_add_f32_e32 v80, v170, v80
	v_pk_mul_f32 v[172:173], v[40:41], v[40:41]
	v_add_f32_e32 v80, v171, v80
	v_add_f32_e32 v80, v172, v80
	v_pk_mul_f32 v[174:175], v[42:43], v[42:43]
	v_add_f32_e32 v80, v173, v80
	v_mbcnt_lo_u32_b32 v81, -1, 0
	v_mbcnt_hi_u32_b32 v81, -1, v81
	v_add_f32_e32 v80, v174, v80
	v_lshlrev_b32_e32 v81, 2, v81
	v_add_f32_e32 v80, v175, v80
	v_xor_b32_e32 v82, 0x80, v81
	ds_bpermute_b32 v82, v82, v80
	v_xor_b32_e32 v83, 8, v81
	s_mov_b32 s0, 0x800000
	s_nop 0
	v_pk_add_f32 v[84:85], v[96:97], 1.0 op_sel_hi:[1,0]
	v_pk_add_f32 v[86:87], v[98:99], 1.0 op_sel_hi:[1,0]
	s_waitcnt lgkmcnt(0)
	v_add_f32_e32 v80, v80, v82
	v_xor_b32_e32 v82, 64, v81
	ds_bpermute_b32 v82, v82, v80
	s_waitcnt lgkmcnt(0)
	v_add_f32_e32 v80, v80, v82
	v_xor_b32_e32 v82, 32, v81
	ds_bpermute_b32 v82, v82, v80
	s_waitcnt lgkmcnt(0)
	v_add_f32_e32 v80, v80, v82
	v_xor_b32_e32 v82, 16, v81
	ds_bpermute_b32 v82, v82, v80
	v_xor_b32_e32 v81, 4, v81
	s_waitcnt lgkmcnt(0)
	v_add_f32_e32 v80, v80, v82
	ds_bpermute_b32 v82, v83, v80
	s_waitcnt lgkmcnt(0)
	v_add_f32_e32 v82, v80, v82
	ds_bpermute_b32 v83, v81, v82
	s_nop 0
	v_pk_add_f32 v[80:81], v[104:105], 1.0 op_sel_hi:[1,0]
	s_waitcnt lgkmcnt(0)
	v_add_f32_e32 v82, v82, v83
	v_fmamk_f32 v82, v82, 0x3a800000, v192
	v_mul_f32_e32 v83, 0x4b800000, v82
	v_cmp_gt_f32_e32 vcc, s0, v82
	s_nop 1
	v_cndmask_b32_e32 v82, v82, v83, vcc
	v_rsq_f32_e32 v168, v82
	v_pk_add_f32 v[82:83], v[106:107], 1.0 op_sel_hi:[1,0]
	v_mul_f32_e32 v169, 0x45800000, v168
	v_cndmask_b32_e32 v168, v168, v169, vcc
	v_pk_mul_f32 v[32:33], v[32:33], v[168:169] op_sel_hi:[1,0]
	v_pk_mul_f32 v[34:35], v[34:35], v[168:169] op_sel_hi:[1,0]
	v_pk_mul_f32 v[36:37], v[36:37], v[168:169] op_sel_hi:[1,0]
	v_pk_mul_f32 v[38:39], v[38:39], v[168:169] op_sel_hi:[1,0]
	v_pk_mul_f32 v[32:33], v[12:13], v[32:33]
	v_pk_mul_f32 v[34:35], v[14:15], v[34:35]
	v_pk_mul_f32 v[36:37], v[0:1], v[36:37]
	v_pk_mul_f32 v[38:39], v[2:3], v[38:39]
	v_pk_fma_f32 v[32:33], v[80:81], v[32:33], v[92:93]
	v_pk_fma_f32 v[34:35], v[82:83], v[34:35], v[94:95]
	v_pk_fma_f32 v[36:37], v[84:85], v[36:37], v[88:89]
	v_pk_fma_f32 v[38:39], v[86:87], v[38:39], v[90:91]
	v_cvt_pk_bf16_f32 v32, v32, v33
	v_cvt_pk_bf16_f32 v33, v34, v35
	v_cvt_pk_bf16_f32 v34, v36, v37
	v_cvt_pk_bf16_f32 v35, v38, v39
	global_store_dwordx4 v[186:187], v[32:35], off offset:-1024
	v_pk_mul_f32 v[36:37], v[46:47], v[168:169] op_sel_hi:[1,0]
	v_pk_mul_f32 v[38:39], v[40:41], v[168:169] op_sel_hi:[1,0]
	v_pk_mul_f32 v[34:35], v[44:45], v[168:169] op_sel_hi:[1,0]
	v_pk_add_f32 v[32:33], v[132:133], 1.0 op_sel_hi:[1,0]
	v_pk_mul_f32 v[34:35], v[28:29], v[34:35]
	v_pk_mul_f32 v[36:37], v[30:31], v[36:37]
	v_pk_fma_f32 v[32:33], v[32:33], v[34:35], v[108:109]
	v_pk_add_f32 v[34:35], v[134:135], 1.0 op_sel_hi:[1,0]
	v_pk_mul_f32 v[38:39], v[16:17], v[38:39]
	v_pk_fma_f32 v[34:35], v[34:35], v[36:37], v[110:111]
	v_pk_add_f32 v[36:37], v[116:117], 1.0 op_sel_hi:[1,0]
	v_pk_mul_f32 v[40:41], v[42:43], v[168:169] op_sel_hi:[1,0]
	v_pk_fma_f32 v[36:37], v[36:37], v[38:39], v[100:101]
	v_pk_add_f32 v[38:39], v[118:119], 1.0 op_sel_hi:[1,0]
	v_pk_mul_f32 v[40:41], v[18:19], v[40:41]
	v_cvt_pk_bf16_f32 v32, v32, v33
	v_pk_fma_f32 v[38:39], v[38:39], v[40:41], v[102:103]
	v_cvt_pk_bf16_f32 v33, v34, v35
	v_cvt_pk_bf16_f32 v34, v36, v37
	v_cvt_pk_bf16_f32 v35, v38, v39
	global_store_dwordx4 v[186:187], v[32:35], off
	s_branch .LBB0_1003
.LBB0_1027:
	s_nop 0
	v_lshlrev_b32_e32 v32, 16, v172
	v_and_b32_e32 v33, 0xffff0000, v172
	v_lshlrev_b32_e32 v34, 16, v173
	v_and_b32_e32 v35, 0xffff0000, v173
	v_lshlrev_b32_e32 v36, 16, v174
	v_and_b32_e32 v37, 0xffff0000, v174
	v_lshlrev_b32_e32 v38, 16, v175
	v_and_b32_e32 v39, 0xffff0000, v175
	s_and_b64 vcc, exec, s[10:11]
	s_cbranch_vccnz .LBB0_1006
.LBB0_1028:
	s_nop 0
	v_lshlrev_b32_e32 v44, 16, v168
	v_and_b32_e32 v45, 0xffff0000, v168
	v_lshlrev_b32_e32 v46, 16, v169
	v_and_b32_e32 v47, 0xffff0000, v169
	v_lshlrev_b32_e32 v40, 16, v170
	v_and_b32_e32 v41, 0xffff0000, v170
	v_lshlrev_b32_e32 v42, 16, v171
	v_and_b32_e32 v43, 0xffff0000, v171
	s_branch .LBB0_1006
